# P2 epilogue stores sc0 nt
# baseline (speedup 1.0000x reference)
; __device__ __forceinline__ unsigned cvt_pk_bf16(float lo, float hi) { unsigned r; asm volatile("v_cvt_pk_bf16_f32 %0, %1, %2" : "=v"(r) : "v"(lo), "v"(hi)); return r; }
;     __device__ __forceinline__ void operator()(const f32x4 (&acc)[2][2][4][2], const Unit& u, int wr, int wc, int fr, int fq) const {
;     ...
;             bf16_t* base; int ld, ct; float sc = 1.f;
;             if (pn < 4) { base = Q; ld = 1024; ct = pn; sc = qscale; } else if (pn < 8) { base = Kb; ld = 1024; ct = pn - 4; } else if (pn < 12) { base = V; ld = 1024; ct = pn - 8; }
;             else if (pn < 14) { base = U; ld = 512; ct = pn - 12; } else { base = G; ld = 2048; ct = pn - 14; }
;             const int row0 = u.pm * BM + wr * 64 + fr, col0 = ct * 256 + wc * 32 + 8 * fq;
; #pragma unroll
;             for (int ai = 0; ai < 2; ++ai)
; #pragma unroll
;                 for (int m = 0; m < 4; ++m) { bf16_t* rowp = base + (size_t)(row0 + ai * HALF + m * 16) * ld + col0;
; #pragma unroll
;                     for (int bj = 0; bj < 2; ++bj) { const f32x4 v0 = acc[ai][bj][m][0] * sc, v1 = acc[ai][bj][m][1] * sc;
;                         u32x4 w; w.x = cvt_pk_bf16(v0[0], v0[1]); w.y = cvt_pk_bf16(v0[2], v0[3]); w.z = cvt_pk_bf16(v1[0], v1[1]); w.w = cvt_pk_bf16(v1[2], v1[3]);
;                         __builtin_nontemporal_store(w, (u32x4*)(rowp + bj * HALF)); } }
.LBB0_215:
	s_cmp_lt_u32 s73, 14
	s_cselect_b64 s[60:61], -1, 0
	s_and_b64 s[66:67], s[60:61], exec
	s_cselect_b32 s13, -12, -14
	s_add_i32 s13, s13, s73
	s_and_b64 s[60:61], s[60:61], exec
	s_cselect_b32 s15, s1, s21
	s_cselect_b32 s33, s0, s20
	v_lshl_add_u32 v148, s58, 8, v150
	v_mov_b32_e32 v146, s33
	s_waitcnt lgkmcnt(0)
	v_mov_b32_e32 v147, s15
	v_lshl_or_b32 v162, s13, 8, v158
	v_mov_b32_e32 v163, v137
	v_ashrrev_i32_e32 v149, 31, v148
	s_cselect_b32 s13, 9, 11
	v_lshl_add_u64 v[146:147], v[162:163], 1, v[146:147]
	v_lshlrev_b64 v[162:163], s13, v[148:149]
	v_lshl_add_u64 v[166:167], v[162:163], 1, v[146:147]
	v_cvt_pk_bf16_f32 v162, v124, v125
	v_cvt_pk_bf16_f32 v163, v126, v127
	v_cvt_pk_bf16_f32 v164, v120, v121
	v_cvt_pk_bf16_f32 v165, v122, v123
	global_store_dwordx4 v[166:167], v[162:165], off sc0 nt
	s_nop 1
	v_cvt_pk_bf16_f32 v162, v68, v69
	v_cvt_pk_bf16_f32 v163, v70, v71
	v_cvt_pk_bf16_f32 v164, v64, v65
	v_cvt_pk_bf16_f32 v165, v66, v67
	global_store_dwordx4 v[166:167], v[162:165], off offset:256 sc0 nt
	s_nop 1
	v_or_b32_e32 v162, 16, v148
	v_ashrrev_i32_e32 v163, 31, v162
	v_lshlrev_b64 v[162:163], s13, v[162:163]
	v_lshl_add_u64 v[166:167], v[162:163], 1, v[146:147]
	v_cvt_pk_bf16_f32 v162, v116, v117
	v_cvt_pk_bf16_f32 v163, v118, v119
	v_cvt_pk_bf16_f32 v164, v112, v113
	v_cvt_pk_bf16_f32 v165, v114, v115
	global_store_dwordx4 v[166:167], v[162:165], off sc0 nt
	s_nop 1
	v_cvt_pk_bf16_f32 v162, v56, v57
	v_cvt_pk_bf16_f32 v163, v58, v59
	v_cvt_pk_bf16_f32 v164, v48, v49
	v_cvt_pk_bf16_f32 v165, v50, v51
	global_store_dwordx4 v[166:167], v[162:165], off offset:256 sc0 nt
	s_nop 1
	v_or_b32_e32 v162, 32, v148
	v_ashrrev_i32_e32 v163, 31, v162
	v_lshlrev_b64 v[162:163], s13, v[162:163]
	v_lshl_add_u64 v[166:167], v[162:163], 1, v[146:147]
	v_cvt_pk_bf16_f32 v162, v108, v109
	v_cvt_pk_bf16_f32 v163, v110, v111
	v_cvt_pk_bf16_f32 v164, v104, v105
	v_cvt_pk_bf16_f32 v165, v106, v107
	global_store_dwordx4 v[166:167], v[162:165], off sc0 nt
	s_nop 1
	v_cvt_pk_bf16_f32 v162, v44, v45
	v_cvt_pk_bf16_f32 v163, v46, v47
	v_cvt_pk_bf16_f32 v164, v40, v41
	v_cvt_pk_bf16_f32 v165, v42, v43
	global_store_dwordx4 v[166:167], v[162:165], off offset:256 sc0 nt
	s_nop 1
	v_or_b32_e32 v162, 48, v148
	v_ashrrev_i32_e32 v163, 31, v162
	v_lshlrev_b64 v[162:163], s13, v[162:163]
	v_lshl_add_u64 v[166:167], v[162:163], 1, v[146:147]
	v_cvt_pk_bf16_f32 v162, v100, v101
	v_cvt_pk_bf16_f32 v163, v102, v103
	v_cvt_pk_bf16_f32 v164, v96, v97
	v_cvt_pk_bf16_f32 v165, v98, v99
	global_store_dwordx4 v[166:167], v[162:165], off sc0 nt
	s_nop 1
	v_cvt_pk_bf16_f32 v162, v36, v37
	v_cvt_pk_bf16_f32 v163, v38, v39
	v_cvt_pk_bf16_f32 v164, v32, v33
	v_cvt_pk_bf16_f32 v165, v34, v35
	global_store_dwordx4 v[166:167], v[162:165], off offset:256 sc0 nt
	s_nop 1
	v_add_u32_e32 v162, 0x80, v148
	v_ashrrev_i32_e32 v163, 31, v162
	v_lshlrev_b64 v[162:163], s13, v[162:163]
	v_lshl_add_u64 v[166:167], v[162:163], 1, v[146:147]
	v_cvt_pk_bf16_f32 v162, v92, v93
	v_cvt_pk_bf16_f32 v163, v94, v95
	v_cvt_pk_bf16_f32 v164, v88, v89
	v_cvt_pk_bf16_f32 v165, v90, v91
	global_store_dwordx4 v[166:167], v[162:165], off sc0 nt
	s_nop 1
	v_cvt_pk_bf16_f32 v162, v28, v29
	v_cvt_pk_bf16_f32 v163, v30, v31
	v_cvt_pk_bf16_f32 v164, v24, v25
	v_cvt_pk_bf16_f32 v165, v26, v27
	global_store_dwordx4 v[166:167], v[162:165], off offset:256 sc0 nt
	s_nop 1
	v_add_u32_e32 v162, 0x90, v148
	v_ashrrev_i32_e32 v163, 31, v162
	v_lshlrev_b64 v[162:163], s13, v[162:163]
	v_lshl_add_u64 v[166:167], v[162:163], 1, v[146:147]
	v_cvt_pk_bf16_f32 v162, v84, v85
	v_cvt_pk_bf16_f32 v163, v86, v87
	v_cvt_pk_bf16_f32 v164, v80, v81
	v_cvt_pk_bf16_f32 v165, v82, v83
	global_store_dwordx4 v[166:167], v[162:165], off sc0 nt
	s_nop 1
	v_cvt_pk_bf16_f32 v162, v20, v21
	v_cvt_pk_bf16_f32 v163, v22, v23
	v_cvt_pk_bf16_f32 v164, v16, v17
	v_cvt_pk_bf16_f32 v165, v18, v19
	global_store_dwordx4 v[166:167], v[162:165], off offset:256 sc0 nt
	s_nop 1
	v_add_u32_e32 v162, 0xa0, v148
	v_ashrrev_i32_e32 v163, 31, v162
	v_lshlrev_b64 v[162:163], s13, v[162:163]
	v_add_u32_e32 v148, 0xb0, v148
	v_lshl_add_u64 v[166:167], v[162:163], 1, v[146:147]
	v_cvt_pk_bf16_f32 v162, v76, v77
	v_cvt_pk_bf16_f32 v163, v78, v79
	v_ashrrev_i32_e32 v149, 31, v148
	v_cvt_pk_bf16_f32 v164, v72, v73
	v_cvt_pk_bf16_f32 v165, v74, v75
	global_store_dwordx4 v[166:167], v[162:165], off sc0 nt
	v_lshlrev_b64 v[148:149], s13, v[148:149]
	s_nop 0
	v_cvt_pk_bf16_f32 v162, v12, v13
	v_cvt_pk_bf16_f32 v163, v14, v15
	v_cvt_pk_bf16_f32 v164, v8, v9
	v_cvt_pk_bf16_f32 v165, v10, v11
	global_store_dwordx4 v[166:167], v[162:165], off offset:256 sc0 nt
	s_nop 1
	v_lshl_add_u64 v[162:163], v[148:149], 1, v[146:147]
	v_cvt_pk_bf16_f32 v146, v60, v61
	v_cvt_pk_bf16_f32 v147, v62, v63
	v_cvt_pk_bf16_f32 v148, v52, v53
	v_cvt_pk_bf16_f32 v149, v54, v55
	global_store_dwordx4 v[162:163], v[146:149], off sc0 nt
	s_nop 1
	v_cvt_pk_bf16_f32 v146, v4, v5
	v_cvt_pk_bf16_f32 v147, v6, v7
	v_cvt_pk_bf16_f32 v148, v0, v1
	v_cvt_pk_bf16_f32 v149, v2, v3
	global_store_dwordx4 v[162:163], v[146:149], off offset:256 sc0 nt
	s_cbranch_execnz .LBB0_202

; __device__ __forceinline__ unsigned cvt_pk_bf16(float lo, float hi) { unsigned r; asm volatile("v_cvt_pk_bf16_f32 %0, %1, %2" : "=v"(r) : "v"(lo), "v"(hi)); return r; }
;     __device__ __forceinline__ void operator()(const f32x4 (&acc)[2][2][4][2], const Unit& u, int wr, int wc, int fr, int fq) const {
;     ...
;         if (HEADMAJOR && pn < 12) {
;             bf16_t* base; int ct; float sc = 1.f;
;             if (pn < 4) { base = Q; ct = pn; sc = qscale; } else if (pn < 8) { base = Kb; ct = pn - 4; } else { base = V; ct = pn - 8; }
;             const int b = u.pm >> 3, t0 = (u.pm & 7) * BM + wr * 64 + fr;
; #pragma unroll
;             for (int bj = 0; bj < 2; ++bj) { bf16_t* hb = base + ((size_t)((b * 8 + 2 * ct + bj) * 2048 + t0)) * 128 + wc * 32 + 8 * fq;
; #pragma unroll
;                 for (int ai = 0; ai < 2; ++ai)
; #pragma unroll
;                     for (int m = 0; m < 4; ++m) { const f32x4 v0 = acc[ai][bj][m][0] * sc, v1 = acc[ai][bj][m][1] * sc;
;                         u32x4 w; w.x = cvt_pk_bf16(v0[0], v0[1]); w.y = cvt_pk_bf16(v0[2], v0[3]); w.z = cvt_pk_bf16(v1[0], v1[1]); w.w = cvt_pk_bf16(v1[2], v1[3]);
;                         __builtin_nontemporal_store(w, (u32x4*)(hb + (ai * HALF + m * 16) * 128)); } }
.LBB0_223:
	s_lshl_b32 s13, s58, 8
	s_and_b32 s13, s13, 0x700
	s_add_u32 s66, s66, s22
	s_addc_u32 s67, s67, 0
	s_lshl_b32 s33, s58, 11
	s_lshl_b32 s15, s73, 12
	s_and_b32 s33, s33, 0xffffc000
	s_add_i32 s15, s15, s33
	s_or_b32 s13, s15, s13
	v_add_u32_e32 v148, s13, v150
	v_ashrrev_i32_e32 v149, 31, v148
	s_waitcnt lgkmcnt(0)
	v_lshl_add_u64 v[146:147], s[66:67], 0, v[136:137]
	v_lshlrev_b64 v[162:163], 8, v[148:149]
	v_lshl_add_u64 v[162:163], v[146:147], 0, v[162:163]
	v_pk_mul_f32 v[126:127], v[126:127], s[60:61] op_sel_hi:[1,0]
	v_pk_mul_f32 v[124:125], v[124:125], s[60:61] op_sel_hi:[1,0]
	v_pk_mul_f32 v[164:165], v[122:123], s[60:61] op_sel_hi:[1,0]
	v_pk_mul_f32 v[122:123], v[120:121], s[60:61] op_sel_hi:[1,0]
	v_cvt_pk_bf16_f32 v120, v124, v125
	v_cvt_pk_bf16_f32 v121, v126, v127
	v_pk_mul_f32 v[116:117], v[116:117], s[60:61] op_sel_hi:[1,0]
	v_cvt_pk_bf16_f32 v122, v122, v123
	v_cvt_pk_bf16_f32 v123, v164, v165
	global_store_dwordx4 v[162:163], v[120:123], off sc0 nt
	v_pk_mul_f32 v[118:119], v[118:119], s[60:61] op_sel_hi:[1,0]
	v_pk_mul_f32 v[110:111], v[110:111], s[60:61] op_sel_hi:[1,0]
	v_pk_mul_f32 v[120:121], v[114:115], s[60:61] op_sel_hi:[1,0]
	v_pk_mul_f32 v[114:115], v[112:113], s[60:61] op_sel_hi:[1,0]
	v_cvt_pk_bf16_f32 v112, v116, v117
	v_add_co_u32_e32 v116, vcc, s89, v162
	v_cvt_pk_bf16_f32 v113, v118, v119
	v_cvt_pk_bf16_f32 v114, v114, v115
	v_cvt_pk_bf16_f32 v115, v120, v121
	v_pk_mul_f32 v[108:109], v[108:109], s[60:61] op_sel_hi:[1,0]
	s_nop 0
	v_addc_co_u32_e32 v117, vcc, 0, v163, vcc
	global_store_dwordx4 v[116:117], v[112:115], off offset:-4096 sc0 nt
	v_pk_mul_f32 v[100:101], v[100:101], s[60:61] op_sel_hi:[1,0]
	v_pk_mul_f32 v[102:103], v[102:103], s[60:61] op_sel_hi:[1,0]
	v_pk_mul_f32 v[112:113], v[106:107], s[60:61] op_sel_hi:[1,0]
	v_pk_mul_f32 v[106:107], v[104:105], s[60:61] op_sel_hi:[1,0]
	v_cvt_pk_bf16_f32 v104, v108, v109
	v_cvt_pk_bf16_f32 v105, v110, v111
	v_pk_mul_f32 v[92:93], v[92:93], s[60:61] op_sel_hi:[1,0]
	v_cvt_pk_bf16_f32 v106, v106, v107
	v_cvt_pk_bf16_f32 v107, v112, v113
	global_store_dwordx4 v[116:117], v[104:107], off sc0 nt
	v_pk_mul_f32 v[94:95], v[94:95], s[60:61] op_sel_hi:[1,0]
	v_pk_mul_f32 v[86:87], v[86:87], s[60:61] op_sel_hi:[1,0]
	v_pk_mul_f32 v[104:105], v[98:99], s[60:61] op_sel_hi:[1,0]
	v_pk_mul_f32 v[98:99], v[96:97], s[60:61] op_sel_hi:[1,0]
	v_cvt_pk_bf16_f32 v96, v100, v101
	v_add_co_u32_e32 v100, vcc, s23, v162
	v_cvt_pk_bf16_f32 v97, v102, v103
	v_cvt_pk_bf16_f32 v98, v98, v99
	v_cvt_pk_bf16_f32 v99, v104, v105
	v_pk_mul_f32 v[84:85], v[84:85], s[60:61] op_sel_hi:[1,0]
	s_nop 0
	v_addc_co_u32_e32 v101, vcc, 0, v163, vcc
	global_store_dwordx4 v[100:101], v[96:99], off sc0 nt
	v_pk_mul_f32 v[76:77], v[76:77], s[60:61] op_sel_hi:[1,0]
	s_mov_b32 s13, 0xb000
	v_pk_mul_f32 v[96:97], v[90:91], s[60:61] op_sel_hi:[1,0]
	v_pk_mul_f32 v[90:91], v[88:89], s[60:61] op_sel_hi:[1,0]
	v_cvt_pk_bf16_f32 v88, v92, v93
	v_add_co_u32_e32 v92, vcc, s72, v162
	v_cvt_pk_bf16_f32 v89, v94, v95
	v_cvt_pk_bf16_f32 v90, v90, v91
	v_cvt_pk_bf16_f32 v91, v96, v97
	v_pk_mul_f32 v[78:79], v[78:79], s[60:61] op_sel_hi:[1,0]
	s_nop 0
	v_addc_co_u32_e32 v93, vcc, 0, v163, vcc
	global_store_dwordx4 v[92:93], v[88:91], off offset:-4096 sc0 nt
	v_pk_mul_f32 v[60:61], v[60:61], s[60:61] op_sel_hi:[1,0]
	v_pk_mul_f32 v[62:63], v[62:63], s[60:61] op_sel_hi:[1,0]
	v_pk_mul_f32 v[88:89], v[82:83], s[60:61] op_sel_hi:[1,0]
	v_pk_mul_f32 v[82:83], v[80:81], s[60:61] op_sel_hi:[1,0]
	v_cvt_pk_bf16_f32 v80, v84, v85
	v_cvt_pk_bf16_f32 v81, v86, v87
	v_pk_mul_f32 v[64:65], v[64:65], s[60:61] op_sel_hi:[1,0]
	v_cvt_pk_bf16_f32 v82, v82, v83
	v_cvt_pk_bf16_f32 v83, v88, v89
	global_store_dwordx4 v[92:93], v[80:83], off sc0 nt
	v_pk_mul_f32 v[46:47], v[46:47], s[60:61] op_sel_hi:[1,0]
	v_pk_mul_f32 v[44:45], v[44:45], s[60:61] op_sel_hi:[1,0]
	v_pk_mul_f32 v[80:81], v[74:75], s[60:61] op_sel_hi:[1,0]
	v_pk_mul_f32 v[74:75], v[72:73], s[60:61] op_sel_hi:[1,0]
	v_cvt_pk_bf16_f32 v72, v76, v77
	v_add_co_u32_e32 v76, vcc, s13, v162
	v_cvt_pk_bf16_f32 v73, v78, v79
	v_cvt_pk_bf16_f32 v74, v74, v75
	v_cvt_pk_bf16_f32 v75, v80, v81
	v_pk_mul_f32 v[36:37], v[36:37], s[60:61] op_sel_hi:[1,0]
	s_nop 0
	v_addc_co_u32_e32 v77, vcc, 0, v163, vcc
; __device__ __forceinline__ unsigned cvt_pk_bf16(float lo, float hi) { unsigned r; asm volatile("v_cvt_pk_bf16_f32 %0, %1, %2" : "=v"(r) : "v"(lo), "v"(hi)); return r; }
;     __device__ __forceinline__ void operator()(const f32x4 (&acc)[2][2][4][2], const Unit& u, int wr, int wc, int fr, int fq) const {
;     ...
;             for (int bj = 0; bj < 2; ++bj) { bf16_t* hb = base + ((size_t)((b * 8 + 2 * ct + bj) * 2048 + t0)) * 128 + wc * 32 + 8 * fq;
; #pragma unroll
;                 for (int ai = 0; ai < 2; ++ai)
; #pragma unroll
;                     for (int m = 0; m < 4; ++m) { const f32x4 v0 = acc[ai][bj][m][0] * sc, v1 = acc[ai][bj][m][1] * sc;
;                         u32x4 w; w.x = cvt_pk_bf16(v0[0], v0[1]); w.y = cvt_pk_bf16(v0[2], v0[3]); w.z = cvt_pk_bf16(v1[0], v1[1]); w.w = cvt_pk_bf16(v1[2], v1[3]);
;                         __builtin_nontemporal_store(w, (u32x4*)(hb + (ai * HALF + m * 16) * 128)); } }
	global_store_dwordx4 v[76:77], v[72:75], off offset:-4096 sc0 nt
	v_pk_mul_f32 v[38:39], v[38:39], s[60:61] op_sel_hi:[1,0]
	v_pk_mul_f32 v[28:29], v[28:29], s[60:61] op_sel_hi:[1,0]
	v_pk_mul_f32 v[72:73], v[54:55], s[60:61] op_sel_hi:[1,0]
	v_pk_mul_f32 v[54:55], v[52:53], s[60:61] op_sel_hi:[1,0]
	v_cvt_pk_bf16_f32 v52, v60, v61
	v_cvt_pk_bf16_f32 v53, v62, v63
	v_pk_mul_f32 v[62:63], v[66:67], s[60:61] op_sel_hi:[1,0]
	v_cvt_pk_bf16_f32 v54, v54, v55
	v_cvt_pk_bf16_f32 v55, v72, v73
	global_store_dwordx4 v[76:77], v[52:55], off sc0 nt
	v_pk_mul_f32 v[30:31], v[30:31], s[60:61] op_sel_hi:[1,0]
	v_pk_mul_f32 v[22:23], v[22:23], s[60:61] op_sel_hi:[1,0]
	v_add_u32_e32 v52, 0x800, v148
	v_ashrrev_i32_e32 v53, 31, v52
	v_lshlrev_b64 v[52:53], 8, v[52:53]
	v_lshl_add_u64 v[60:61], v[146:147], 0, v[52:53]
	v_pk_mul_f32 v[52:53], v[68:69], s[60:61] op_sel_hi:[1,0]
	v_pk_mul_f32 v[54:55], v[70:71], s[60:61] op_sel_hi:[1,0]
	v_cvt_pk_bf16_f32 v52, v52, v53
	v_pk_mul_f32 v[20:21], v[20:21], s[60:61] op_sel_hi:[1,0]
	v_cvt_pk_bf16_f32 v53, v54, v55
	v_cvt_pk_bf16_f32 v54, v64, v65
	v_cvt_pk_bf16_f32 v55, v62, v63
	global_store_dwordx4 v[60:61], v[52:55], off sc0 nt
	v_pk_mul_f32 v[12:13], v[12:13], s[60:61] op_sel_hi:[1,0]
	s_mov_b32 s13, 0xa000
	v_pk_mul_f32 v[52:53], v[58:59], s[60:61] op_sel_hi:[1,0]
	v_pk_mul_f32 v[54:55], v[56:57], s[60:61] op_sel_hi:[1,0]
	v_pk_mul_f32 v[56:57], v[50:51], s[60:61] op_sel_hi:[1,0]
	v_pk_mul_f32 v[50:51], v[48:49], s[60:61] op_sel_hi:[1,0]
	v_cvt_pk_bf16_f32 v48, v54, v55
	v_cvt_pk_bf16_f32 v49, v52, v53
	v_add_co_u32_e32 v52, vcc, s89, v60
	v_cvt_pk_bf16_f32 v50, v50, v51
	v_cvt_pk_bf16_f32 v51, v56, v57
	v_pk_mul_f32 v[14:15], v[14:15], s[60:61] op_sel_hi:[1,0]
	s_nop 0
	v_addc_co_u32_e32 v53, vcc, 0, v61, vcc
	global_store_dwordx4 v[52:53], v[48:51], off offset:-4096 sc0 nt
	v_pk_mul_f32 v[4:5], v[4:5], s[60:61] op_sel_hi:[1,0]
	v_pk_mul_f32 v[6:7], v[6:7], s[60:61] op_sel_hi:[1,0]
	v_pk_mul_f32 v[48:49], v[42:43], s[60:61] op_sel_hi:[1,0]
	v_pk_mul_f32 v[42:43], v[40:41], s[60:61] op_sel_hi:[1,0]
	v_cvt_pk_bf16_f32 v40, v44, v45
	v_cvt_pk_bf16_f32 v41, v46, v47
	s_nop 0
	v_cvt_pk_bf16_f32 v42, v42, v43
	v_cvt_pk_bf16_f32 v43, v48, v49
	global_store_dwordx4 v[52:53], v[40:43], off sc0 nt
	s_nop 1
	v_pk_mul_f32 v[40:41], v[34:35], s[60:61] op_sel_hi:[1,0]
	v_pk_mul_f32 v[34:35], v[32:33], s[60:61] op_sel_hi:[1,0]
	v_cvt_pk_bf16_f32 v32, v36, v37
	v_add_co_u32_e32 v36, vcc, s23, v60
	v_cvt_pk_bf16_f32 v33, v38, v39
	v_cvt_pk_bf16_f32 v34, v34, v35
	v_cvt_pk_bf16_f32 v35, v40, v41
	s_nop 1
	v_addc_co_u32_e32 v37, vcc, 0, v61, vcc
	global_store_dwordx4 v[36:37], v[32:35], off sc0 nt
	s_nop 1
	v_pk_mul_f32 v[32:33], v[26:27], s[60:61] op_sel_hi:[1,0]
	v_pk_mul_f32 v[26:27], v[24:25], s[60:61] op_sel_hi:[1,0]
	v_cvt_pk_bf16_f32 v24, v28, v29
	v_add_co_u32_e32 v28, vcc, s72, v60
	v_cvt_pk_bf16_f32 v25, v30, v31
	v_cvt_pk_bf16_f32 v26, v26, v27
	v_cvt_pk_bf16_f32 v27, v32, v33
	s_nop 1
	v_addc_co_u32_e32 v29, vcc, 0, v61, vcc
	global_store_dwordx4 v[28:29], v[24:27], off offset:-4096 sc0 nt
	s_nop 1
	v_pk_mul_f32 v[24:25], v[18:19], s[60:61] op_sel_hi:[1,0]
	v_pk_mul_f32 v[18:19], v[16:17], s[60:61] op_sel_hi:[1,0]
	v_cvt_pk_bf16_f32 v16, v20, v21
	v_cvt_pk_bf16_f32 v17, v22, v23
	s_nop 0
	v_cvt_pk_bf16_f32 v18, v18, v19
	v_cvt_pk_bf16_f32 v19, v24, v25
	global_store_dwordx4 v[28:29], v[16:19], off sc0 nt
	s_nop 1
	v_pk_mul_f32 v[16:17], v[10:11], s[60:61] op_sel_hi:[1,0]
	v_pk_mul_f32 v[10:11], v[8:9], s[60:61] op_sel_hi:[1,0]
	v_cvt_pk_bf16_f32 v8, v12, v13
	v_add_co_u32_e32 v12, vcc, s13, v60
	v_cvt_pk_bf16_f32 v9, v14, v15
	v_cvt_pk_bf16_f32 v10, v10, v11
	v_cvt_pk_bf16_f32 v11, v16, v17
	s_nop 1
	v_addc_co_u32_e32 v13, vcc, 0, v61, vcc
	global_store_dwordx4 v[12:13], v[8:11], off sc0 nt
	s_nop 1
	v_pk_mul_f32 v[8:9], v[2:3], s[60:61] op_sel_hi:[1,0]
	v_pk_mul_f32 v[2:3], v[0:1], s[60:61] op_sel_hi:[1,0]
	v_cvt_pk_bf16_f32 v0, v4, v5
	v_add_co_u32_e32 v4, vcc, 0xb000, v60
	v_cvt_pk_bf16_f32 v1, v6, v7
	v_cvt_pk_bf16_f32 v2, v2, v3
	v_cvt_pk_bf16_f32 v3, v8, v9
	s_nop 1
	v_addc_co_u32_e32 v5, vcc, 0, v61, vcc
	global_store_dwordx4 v[4:5], v[0:3], off sc0 nt
	s_andn2_b64 vcc, exec, s[4:5]
	s_mov_b64 s[4:5], -1
	s_cbranch_vccnz .LBB0_193
